# v54 + MLA guarded steady step as its own body: QK MFMAs p0 x6 then p1 x6, p0 softmax arithmetic in the shadow of p1's QK MFMAs, p1's under the first P.V MFMAs (same instructions and math)
# baseline (speedup 1.0000x reference)
.LBB0_1476:
	s_mul_i32 s52, s49, 0x3000
	v_add_u32_e32 v66, s52, v182
	v_add_u32_e32 v67, v66, v184
	v_add_u32_e32 v66, v66, v189
	ds_read_b128 v[82:85], v67
	ds_read_b128 v[158:161], v67 offset:2048
	ds_read_b128 v[162:165], v66
	ds_read_b128 v[150:153], v66 offset:2048
	ds_read_b128 v[146:149], v67 offset:4096
	ds_read_b128 v[142:145], v67 offset:6144
	ds_read_b128 v[138:141], v66 offset:4096
	ds_read_b128 v[134:137], v66 offset:6144
	ds_read_b128 v[130:133], v67 offset:8192
	ds_read_b128 v[126:129], v67 offset:10240
	ds_read_b128 v[122:125], v66 offset:8192
	ds_read_b128 v[154:157], v66 offset:10240
	s_cmp_lg_u32 s101, 0
	s_cbranch_scc1 .Lmla2p
	s_waitcnt lgkmcnt(11)
	v_mfma_f32_32x32x16_bf16 v[66:81], v[82:85], v[98:101], v[50:65]
	s_lshl_b32 s58, s49, 13
	s_waitcnt lgkmcnt(10)
	v_mfma_f32_32x32x16_bf16 v[82:97], v[158:161], v[98:101], v[50:65]
	v_add_u32_e32 v158, s58, v183
	s_add_u32 s26, s54, s24
	s_addc_u32 s27, s55, s25
	s_xor_b32 s57, s49, 1
	s_mul_i32 s56, s57, 0x3000
	s_add_i32 s51, s56, s38
	s_mov_b32 s98, m0
	s_mov_b32 m0, s51
	s_nop 0
	global_load_lds_dwordx4 v1, s[26:27]
	s_mov_b32 m0, s98
	s_and_b64 vcc, exec, s[8:9]
	s_cbranch_vccnz .LBB0_1478
	s_add_i32 s26, s56, s39
	s_mov_b32 s27, m0
	s_mov_b32 m0, s26
	s_nop 0
	global_load_lds_dwordx4 v180, s[22:23]
	s_mov_b32 m0, s27

.Lmla2p:
	s_waitcnt lgkmcnt(11)
	v_mfma_f32_32x32x16_bf16 v[66:81], v[82:85], v[98:101], v[50:65]
	s_lshl_b32 s58, s49, 13
	v_add_u32_e32 v247, s58, v183
	s_waitcnt lgkmcnt(9)
	v_mfma_f32_32x32x16_bf16 v[66:81], v[162:165], v[106:109], v[66:81]
	s_add_u32 s26, s54, s24
	s_addc_u32 s27, s55, s25
	s_xor_b32 s57, s49, 1
	s_mul_i32 s56, s57, 0x3000
	s_add_i32 s51, s56, s38
	s_mov_b32 s98, m0
	s_mov_b32 m0, s51
	s_nop 0
	global_load_lds_dwordx4 v1, s[26:27]
	s_mov_b32 m0, s98
	s_and_b64 vcc, exec, s[8:9]
	s_cbranch_vccnz .Lmla2p_k
	s_add_i32 s26, s56, s39
	s_mov_b32 s27, m0
	s_mov_b32 m0, s26
	s_nop 0
	global_load_lds_dwordx4 v180, s[22:23]
	s_mov_b32 m0, s27
.Lmla2p_k:
	s_waitcnt lgkmcnt(7)
	v_mfma_f32_32x32x16_bf16 v[66:81], v[146:149], v[102:105], v[66:81]
	s_waitcnt lgkmcnt(5)
	v_mfma_f32_32x32x16_bf16 v[66:81], v[138:141], v[114:117], v[66:81]
	s_add_u32 s26, s0, s24
	s_addc_u32 s27, s53, s25
	s_lshl_b32 s51, s57, 13
	s_add_i32 s98, s51, s43
	s_mov_b32 s99, m0
	s_mov_b32 m0, s98
	s_nop 0
	global_load_lds_dwordx4 v181, s[26:27]
	s_mov_b32 m0, s99
	s_waitcnt lgkmcnt(3)
	v_mfma_f32_32x32x16_bf16 v[66:81], v[130:133], v[110:113], v[66:81]
	s_waitcnt lgkmcnt(0)
	v_mfma_f32_32x32x16_bf16 v[66:81], v[122:125], v[118:121], v[66:81]
	ds_read_b64_tr_b16 v[146:147], v247 offset:25600
	ds_read_b64_tr_b16 v[148:149], v247 offset:26112
	ds_read_b64_tr_b16 v[138:139], v247 offset:27648
	ds_read_b64_tr_b16 v[140:141], v247 offset:28160
	ds_read_b64_tr_b16 v[130:131], v247 offset:29696
	ds_read_b64_tr_b16 v[132:133], v247 offset:30208
	ds_read_b64_tr_b16 v[122:123], v247 offset:31744
	ds_read_b64_tr_b16 v[124:125], v247 offset:32256
	v_mfma_f32_32x32x16_bf16 v[82:97], v[158:161], v[98:101], v[50:65]
	v_mfma_f32_32x32x16_bf16 v[82:97], v[150:153], v[106:109], v[82:97]
	ds_read_b64_tr_b16 v[150:151], v247 offset:24576
	ds_read_b64_tr_b16 v[152:153], v247 offset:25088
	s_nop 1
	v_exp_f32_e32 v66, v66
	v_exp_f32_e32 v67, v67
	v_exp_f32_e32 v68, v68
	v_mfma_f32_32x32x16_bf16 v[82:97], v[142:145], v[102:105], v[82:97]
	ds_read_b64_tr_b16 v[142:143], v247 offset:26624
	ds_read_b64_tr_b16 v[144:145], v247 offset:27136
	v_exp_f32_e32 v69, v69
	v_exp_f32_e32 v70, v70
	v_exp_f32_e32 v71, v71
	v_mfma_f32_32x32x16_bf16 v[82:97], v[134:137], v[114:117], v[82:97]
	ds_read_b64_tr_b16 v[134:135], v247 offset:28672
	ds_read_b64_tr_b16 v[136:137], v247 offset:29184
	v_exp_f32_e32 v72, v72
	v_exp_f32_e32 v73, v73
	v_pk_add_f32 v[162:163], v[66:67], v[68:69]
	v_mfma_f32_32x32x16_bf16 v[82:97], v[126:129], v[110:113], v[82:97]
	ds_read_b64_tr_b16 v[126:127], v247 offset:30720
	ds_read_b64_tr_b16 v[128:129], v247 offset:31232
	v_exp_f32_e32 v74, v74
	v_exp_f32_e32 v75, v75
	v_exp_f32_e32 v76, v76
	v_mfma_f32_32x32x16_bf16 v[82:97], v[154:157], v[118:121], v[82:97]
	v_exp_f32_e32 v77, v77
	v_exp_f32_e32 v78, v78
	v_exp_f32_e32 v79, v79
	v_exp_f32_e32 v80, v80
	v_exp_f32_e32 v81, v81
	v_pk_add_f32 v[164:165], v[70:71], v[72:73]
	v_pk_add_f32 v[158:159], v[162:163], v[164:165]
	v_cvt_pk_bf16_f32 v66, v66, v67
	v_cvt_pk_bf16_f32 v67, v68, v69
	v_cvt_pk_bf16_f32 v68, v70, v71
	v_cvt_pk_bf16_f32 v69, v72, v73
	v_pk_add_f32 v[162:163], v[74:75], v[76:77]
	v_pk_add_f32 v[164:165], v[78:79], v[80:81]
	v_pk_add_f32 v[160:161], v[162:163], v[164:165]
	v_cvt_pk_bf16_f32 v70, v74, v75
	v_cvt_pk_bf16_f32 v71, v76, v77
	v_cvt_pk_bf16_f32 v72, v78, v79
	v_cvt_pk_bf16_f32 v73, v80, v81
	s_waitcnt lgkmcnt(6)
	v_mfma_f32_32x32x16_bf16 v[18:33], v[66:69], v[150:153], v[18:33]
	v_exp_f32_e32 v82, v82
	v_exp_f32_e32 v83, v83
	v_exp_f32_e32 v84, v84
	s_waitcnt lgkmcnt(2)
	v_mfma_f32_32x32x16_bf16 v[34:49], v[66:69], v[134:137], v[34:49]
	v_exp_f32_e32 v85, v85
	v_exp_f32_e32 v86, v86
	v_exp_f32_e32 v87, v87
	v_mfma_f32_32x32x16_bf16 v[18:33], v[70:73], v[146:149], v[18:33]
	v_exp_f32_e32 v88, v88
	v_exp_f32_e32 v89, v89
	v_pk_add_f32 v[162:163], v[82:83], v[84:85]
	v_mfma_f32_32x32x16_bf16 v[34:49], v[70:73], v[130:133], v[34:49]
	v_pk_add_f32 v[164:165], v[86:87], v[88:89]
	v_pk_add_f32 v[154:155], v[162:163], v[164:165]
	v_cvt_pk_bf16_f32 v74, v82, v83
	v_cvt_pk_bf16_f32 v75, v84, v85
	v_cvt_pk_bf16_f32 v76, v86, v87
	v_cvt_pk_bf16_f32 v77, v88, v89
	v_exp_f32_e32 v90, v90
	v_exp_f32_e32 v91, v91
	v_mfma_f32_32x32x16_bf16 v[18:33], v[74:77], v[142:145], v[18:33]
	v_exp_f32_e32 v92, v92
	v_exp_f32_e32 v93, v93
	v_exp_f32_e32 v94, v94
	s_waitcnt lgkmcnt(0)
	v_mfma_f32_32x32x16_bf16 v[34:49], v[74:77], v[126:129], v[34:49]
	v_exp_f32_e32 v95, v95
	v_exp_f32_e32 v96, v96
	v_exp_f32_e32 v97, v97
	v_pk_add_f32 v[162:163], v[90:91], v[92:93]
	v_pk_add_f32 v[164:165], v[94:95], v[96:97]
	v_pk_add_f32 v[156:157], v[162:163], v[164:165]
	v_cvt_pk_bf16_f32 v78, v90, v91
	v_cvt_pk_bf16_f32 v79, v92, v93
	v_cvt_pk_bf16_f32 v80, v94, v95
	v_cvt_pk_bf16_f32 v81, v96, v97
	v_pk_add_f32 v[158:159], v[158:159], v[160:161]
	s_add_u32 s24, s24, 0x10000
	s_addc_u32 s25, s25, 0
	v_mfma_f32_32x32x16_bf16 v[18:33], v[78:81], v[138:141], v[18:33]
	v_pk_add_f32 v[154:155], v[154:155], v[156:157]
	s_add_u32 s22, s22, 0x1000
	s_addc_u32 s23, s23, 0
	v_mfma_f32_32x32x16_bf16 v[34:49], v[78:81], v[122:125], v[34:49]
	v_pk_add_f32 v[158:159], v[158:159], v[154:155]
	s_waitcnt vmcnt(0) lgkmcnt(0)
	s_barrier
	v_add_f32_e32 v158, v158, v159
	s_cmp_eq_u32 s24, 0x200000
	v_add_f32_e32 v173, v173, v158
	s_cbranch_scc1 .LBB0_1484
	s_mov_b32 s49, s57
	s_branch .LBB0_1476
